# phase 0 work rebalancing: weight-conversion tiles dealt only to the 320 virtual blocks that have no compute_mod item (10 tiles each)
# speedup vs baseline: 1.0038x; 1.0038x over previous
; DI int otid() { int t = threadIdx.x & 255; asm volatile("" : "+v"(t)); return t; }
; DI int oidx(int i) { asm volatile("" : "+s"(i)); return i; }
; DI int VB() { return blockIdx.x * 2 + vhalf(); }
; DN void convert_weights(const Params& p, int l, char* smem) {
;   float* tile68 = (float*)smem;
;   const int tid = otid();
;   const int T_IN = 52 * 16, T_OUT = 16 * 16, T_UP = 88 * 16, T_DN = 16 * 44;
;   const int total = T_IN + T_OUT + T_UP + T_DN;
;   for (int it = VB(); it < total; it += NVB()) {
;     const float* src; int ld, ldd, n0, k0, mode, nvalid; bfr* dst;
;     if (it < T_IN) { int nt = it / 16, kt = it % 16; src = p.in[oidx(8)] + (size_t)l * DM * 3232; ld = 3232; nvalid = 3232; dst = (bfr*)(p.ws + OFF_WIN); ldd = DM; n0 = nt * 64; k0 = kt * 64; mode = 0; }
;     else if (it < T_IN + T_OUT) { int i2 = it - T_IN; int nt = i2 / 16, kt = i2 % 16; src = p.in[oidx(9)] + (size_t)l * DM * DM; ld = DM; nvalid = DM; dst = (bfr*)(p.ws + OFF_WOUT); ldd = DM; n0 = nt * 64; k0 = kt * 64; mode = 0; }
;     else if (it < T_IN + T_OUT + T_UP) { int i2 = it - T_IN - T_OUT; int nt = i2 / 16, kt = i2 % 16; src = p.in[oidx(28)] + (size_t)l * DM * 2 * DFF; ld = 2 * DFF; nvalid = 2 * DFF; dst = (bfr*)(p.ws + OFF_WUP); ldd = DM; n0 = nt * 64; k0 = kt * 64; mode = 1; }
;     else { int i2 = it - T_IN - T_OUT - T_UP; int nt = i2 / 44, kt = i2 % 44; src = p.in[oidx(31)] + (size_t)l * DFF * DM; ld = DM; nvalid = DM; dst = (bfr*)(p.ws + OFF_WDN); ldd = DFF; n0 = nt * 64; k0 = kt * 64; mode = 0; }
; #pragma unroll
;     for (int i = 0; i < 4; ++i) {
;       const int c = tid + 256 * i, kl = c >> 4, n4 = (c & 15) * 4;
;       const int n = n0 + n4;
;       int sc = n;
;       if (mode == 1) { int grp = n >> 8, within = n & 255; sc = ((within >= 128) ? DFF : 0) + grp * 128 + (within & 127); }
;       f32x4v v = {0.f, 0.f, 0.f, 0.f};
;       if (sc < nvalid) v = *(const f32x4v*)(src + (size_t)(k0 + kl) * ld + sc);
;       *(f32x4v*)(&tile68[kl * 68 + n4]) = v;
.LBB0_5:
	v_lshlrev_b32_e32 v2, 2, v16
	v_and_b32_e32 v17, 60, v2
	s_add_i32 s6, 0, 0x21000
	v_and_b32_e32 v2, 12, v79
	s_lshl_b32 s2, s4, 16
	v_add_u32_e32 v18, s6, v2
	v_ashrrev_i32_e32 v20, 4, v16
	s_movk_i32 s6, 0x110
	s_add_i32 s5, s2, 0
	v_mul_lo_u32 v2, v20, s6
	v_lshlrev_b32_e32 v3, 2, v17
	v_add3_u32 v21, s5, v2, v3
	v_add_u32_e32 v2, 0x100, v16
	v_ashrrev_i32_e32 v22, 4, v2
	v_mul_lo_u32 v4, v22, s6
	v_add3_u32 v23, s5, v4, v3
	v_add_u32_e32 v4, 0x200, v16
	v_ashrrev_i32_e32 v24, 4, v4
	v_mul_lo_u32 v4, v24, s6
	v_add3_u32 v25, s5, v4, v3
	v_add_u32_e32 v4, 0x300, v16
	v_ashrrev_i32_e32 v26, 4, v4
	v_mul_lo_u32 v4, v26, s6
	s_waitcnt lgkmcnt(0)
	s_load_dwordx2 s[8:9], s[0:1], 0x108
	v_add3_u32 v27, s5, v4, v3
	v_ashrrev_i32_e32 v3, 3, v16
	v_and_b32_e32 v19, 63, v16
	v_and_b32_e32 v10, -8, v3
	v_or_b32_e32 v3, 7, v3
	v_ashrrev_i32_e32 v2, 3, v2
	v_lshlrev_b32_e32 v5, 2, v19
	v_mul_lo_u32 v3, v3, s6
	v_and_b32_e32 v12, -8, v2
	v_or_b32_e32 v2, 7, v2
	v_mul_lo_u32 v4, v10, s6
	v_add3_u32 v29, s5, v3, v5
	v_mul_lo_u32 v3, v12, s6
	v_mul_lo_u32 v2, v2, s6
	v_add3_u32 v28, s5, v4, v5
	v_add3_u32 v30, s5, v3, v5
	v_add3_u32 v31, s5, v2, v5
	s_load_dword s5, s[0:1], 0x110
	s_waitcnt lgkmcnt(0)
	s_add_u32 s12, s8, 0x1380000
	s_addc_u32 s13, s9, 0
	s_add_u32 s14, s8, 0x880000
	s_addc_u32 s15, s9, 0
	s_add_u32 s16, s8, 0x680000
	s_mov_b32 s4, 0
	v_cmp_eq_u32_e64 s[2:3], 0, v1
	v_ashrrev_i32_e32 v11, 31, v10
	v_ashrrev_i32_e32 v13, 31, v12
	s_addc_u32 s17, s9, 0
	s_lshl_b32 s29, s5, 1
	s_sub_i32 s29, s29, 0xc0
	s_movk_i32 s30, 0x7f
	v_mov_b32_e32 v32, 1
	s_sub_i32 s28, s28, 0xc0
	s_cmp_lt_i32 s28, 0
	s_cbranch_scc1 .LBB0_32
	s_branch .LBB0_7
